# v16 + k=5 attn_merge: the three output-row loads are issued together with the LSE loads (counted vmcnt) instead of after the softmax weights
# speedup vs baseline: 1.0107x; 1.0008x over previous
; __device__ __forceinline__ unsigned pk2(float lo, float hi) { return f2bf(lo) | (f2bf(hi) << 16); }
; __device__ __forceinline__ void attn_merge(const Params& p, int gt, int ngt) {
;     ...
;     for (int idx = gt; idx < T * 32; idx += ngt) { const int m = idx >> 5, c8 = idx & 31, h = c8 >> 3;
;         const float l0 = LSE[(size_t)m * 12 + h], l1 = LSE[(size_t)m * 12 + 4 + h], l2 = LSE[(size_t)m * 12 + 8 + h];
;         const float mx = fmaxf(l0, fmaxf(l1, l2)); float w0 = __expf(l0 - mx), w1 = __expf(l1 - mx), w2 = __expf(l2 - mx); const float inv = 1.f / (w0 + w1 + w2); w0 *= inv; w1 *= inv; w2 *= inv;
;         const bf16* o = QKVX + (size_t)m * 3072 + c8 * 8;
;         const v4u a = *(const v4u*)o, b = *(const v4u*)(o + 256), c = *(const v4u*)(o + 512);
;         v4u r;
;         r.x = pk2(w0 * bflo(a.x) + w1 * bflo(b.x) + w2 * bflo(c.x), w0 * bfhi(a.x) + w1 * bfhi(b.x) + w2 * bfhi(c.x));
;         r.y = pk2(w0 * bflo(a.y) + w1 * bflo(b.y) + w2 * bflo(c.y), w0 * bfhi(a.y) + w1 * bfhi(b.y) + w2 * bfhi(c.y));
;         r.z = pk2(w0 * bflo(a.z) + w1 * bflo(b.z) + w2 * bflo(c.z), w0 * bfhi(a.z) + w1 * bfhi(b.z) + w2 * bfhi(c.z));
;         r.w = pk2(w0 * bflo(a.w) + w1 * bflo(b.w) + w2 * bflo(c.w), w0 * bfhi(a.w) + w1 * bfhi(b.w) + w2 * bfhi(c.w));
;         *(v4u*)(AT + (size_t)m * 256 + c8 * 8) = r; }
.LBB0_361:
	v_ashrrev_i32_e32 v20, 5, v1
	v_mad_i64_i32 v[8:9], s[8:9], v20, 48, v[6:7]
	global_load_dword v10, v[8:9], off
	global_load_dword v11, v[8:9], off offset:16
	s_nop 0
	global_load_dword v8, v[8:9], off offset:32
	v_mad_i64_i32 v[16:17], s[8:9], v20, s64, v[2:3]
	global_load_dwordx4 v[32:35], v[16:17], off
	global_load_dwordx4 v[36:39], v[16:17], off offset:512
	global_load_dwordx4 v[40:43], v[16:17], off offset:1024
	v_ashrrev_i32_e32 v21, 31, v20
	v_add_u32_e32 v1, s6, v1
	s_mov_b32 s7, 0xfffff
	s_waitcnt vmcnt(3)
	v_max3_f32 v9, v10, v11, v8
	v_sub_f32_e32 v10, v10, v9
	v_mul_f32_e32 v10, 0x3fb8aa3b, v10
	v_exp_f32_e32 v23, v10
	v_sub_f32_e32 v10, v11, v9
	v_mul_f32_e32 v10, 0x3fb8aa3b, v10
	v_sub_f32_e32 v8, v8, v9
	v_exp_f32_e32 v22, v10
	v_mul_f32_e32 v8, 0x3fb8aa3b, v8
	v_exp_f32_e32 v8, v8
	v_add_f32_e32 v9, v23, v22
	v_add_f32_e32 v9, v8, v9
	v_div_scale_f32 v10, s[8:9], v9, v9, 1.0
	v_rcp_f32_e32 v11, v10
	s_nop 0
	v_fma_f32 v12, -v10, v11, 1.0
	v_fmac_f32_e32 v11, v12, v11
	v_div_scale_f32 v12, vcc, 1.0, v9, 1.0
	v_mul_f32_e32 v13, v12, v11
	v_fma_f32 v14, -v10, v13, v12
	v_fmac_f32_e32 v13, v14, v11
	v_fma_f32 v10, -v10, v13, v12
	v_div_fmas_f32 v10, v10, v11, v13
	v_div_fixup_f32 v24, v10, v9, 1.0
	v_mul_f32_e32 v26, v8, v24
	v_pk_mul_f32 v[22:23], v[22:23], v[24:25] op_sel_hi:[1,0]
	v_cmp_lt_i32_e32 vcc, s7, v1
	s_or_b64 s[4:5], vcc, s[4:5]
	s_waitcnt vmcnt(0)
	v_lshlrev_b32_e32 v28, 16, v32
	v_lshlrev_b32_e32 v29, 16, v37
	v_lshlrev_b32_e32 v25, 16, v33
	v_lshlrev_b32_e32 v24, 16, v36
	v_pk_mul_f32 v[28:29], v[22:23], v[28:29] op_sel:[1,0] op_sel_hi:[0,1]
	v_pk_fma_f32 v[24:25], v[22:23], v[24:25], v[28:29]
	v_lshlrev_b32_e32 v29, 16, v41
	v_lshlrev_b32_e32 v28, 16, v40
	v_pk_fma_f32 v[24:25], v[26:27], v[28:29], v[24:25] op_sel_hi:[0,1,1]
	v_and_b32_e32 v29, 0xffff0000, v33
	v_and_b32_e32 v33, 0xffff0000, v37
	v_and_b32_e32 v32, 0xffff0000, v32
	v_and_b32_e32 v28, 0xffff0000, v36
	v_pk_mul_f32 v[32:33], v[22:23], v[32:33] op_sel:[1,0] op_sel_hi:[0,1]
	v_pk_fma_f32 v[32:33], v[22:23], v[28:29], v[32:33]
	v_and_b32_e32 v37, 0xffff0000, v41
	v_and_b32_e32 v36, 0xffff0000, v40
	v_lshlrev_b32_e32 v41, 16, v39
	v_lshlrev_b32_e32 v40, 16, v34
	v_pk_fma_f32 v[32:33], v[26:27], v[36:37], v[32:33] op_sel_hi:[0,1,1]
	v_lshlrev_b32_e32 v37, 16, v35
	v_lshlrev_b32_e32 v36, 16, v38
	v_pk_mul_f32 v[40:41], v[22:23], v[40:41] op_sel:[1,0] op_sel_hi:[0,1]
	v_pk_fma_f32 v[36:37], v[22:23], v[36:37], v[40:41]
	v_lshlrev_b32_e32 v41, 16, v43
	v_lshlrev_b32_e32 v40, 16, v42
	v_pk_fma_f32 v[36:37], v[26:27], v[40:41], v[36:37] op_sel_hi:[0,1,1]
	v_and_b32_e32 v41, 0xffff0000, v35
	v_and_b32_e32 v35, 0xffff0000, v39
	v_and_b32_e32 v34, 0xffff0000, v34
	v_and_b32_e32 v40, 0xffff0000, v38
	v_pk_mul_f32 v[34:35], v[22:23], v[34:35] op_sel:[1,0] op_sel_hi:[0,1]
	v_pk_fma_f32 v[34:35], v[22:23], v[40:41], v[34:35]
	v_and_b32_e32 v39, 0xffff0000, v43
	v_and_b32_e32 v38, 0xffff0000, v42
	v_pk_fma_f32 v[34:35], v[26:27], v[38:39], v[34:35] op_sel_hi:[0,1,1]
	v_bfe_u32 v40, v36, 16, 1
	v_bfe_u32 v41, v37, 16, 1
	v_lshrrev_b32_e32 v38, 16, v38
	v_lshrrev_b32_e32 v39, 16, v39
	v_cvt_pk_bf16_f32 v35, v37, v35
	v_cvt_pk_bf16_f32 v34, v36, v34
	v_lshlrev_b64 v[36:37], 9, v[20:21]
	v_cvt_pk_bf16_f32 v33, v25, v33
	v_cvt_pk_bf16_f32 v32, v24, v32
	v_lshl_add_u64 v[36:37], v[4:5], 0, v[36:37]
	global_store_dwordx4 v[36:37], v[32:35], off
	s_andn2_b64 exec, exec, s[4:5]
	s_cbranch_execnz .LBB0_361
